# nt on P0 f32 weight loads (read once for the bf16 transpose)
# speedup vs baseline: 1.0361x; 1.0056x over previous
; DI unsigned cvt_pk(float lo, float hi) { const f32x2 v = {lo, hi}; return __builtin_bit_cast(unsigned, __builtin_convertvector(v, bf16v2)); }
; DI void p0_weight_tile(const float* W, bf16_t* Bt, int N, const float* g, bool permute, int t, int lane) {
;     const int ntn = N / 64, k0 = (t / ntn) * 64, n0 = (t % ntn) * 64;
;     const int nlog = n0 + lane;
;     const int c = permute ? ((nlog & ~255) | (((nlog >> 5) & 1) << 7) | (((nlog >> 6) & 3) << 5) | (nlog & 31)) : nlog;
;     const float* src = W + (size_t)k0 * N + nlog;
;     bf16_t* dst = Bt + (size_t)c * 1024 + k0;
; #pragma unroll
;     for (int hh = 0; hh < 2; ++hh) {
;         float v[32];
; #pragma unroll
;         for (int k = 0; k < 32; ++k) v[k] = src[(size_t)(32 * hh + k) * N];
; #pragma unroll
;         for (int k = 0; k < 32; ++k) v[k] *= (g ? g[k0 + 32 * hh + k] : 1.0f);
; #pragma unroll
;         for (int j = 0; j < 4; ++j) {
;             u32x4 w; w.x = cvt_pk(v[8 * j], v[8 * j + 1]); w.y = cvt_pk(v[8 * j + 2], v[8 * j + 3]); w.z = cvt_pk(v[8 * j + 4], v[8 * j + 5]); w.w = cvt_pk(v[8 * j + 6], v[8 * j + 7]);
;             *(u32x4*)(dst + 32 * hh + 8 * j) = w;
;         }
; DI void p0_prologue(const Params& P, LAS unsigned char* lds) {
;     ...
;             if (t < T0) p0_weight_tile(P.w_in_even, (bf16_t*)(ws + WS_BT0), N_IN0, P.norm_even, true, t, lane);
;             else if (t < T0 + T1) p0_weight_tile(P.w_out_even, (bf16_t*)(ws + WS_BT1), DM, nullptr, false, t - T0, lane);
;             else if (t < T0 + T1 + T2) p0_weight_tile(P.w_in_odd, (bf16_t*)(ws + WS_BT2), N_IN1, P.norm_odd, true, t - T0 - T1, lane);
;             else p0_weight_tile(P.w_out_odd, (bf16_t*)(ws + WS_BT3), DM, nullptr, false, t - T0 - T1 - T2, lane);
.LBB0_41:
	s_movk_i32 s0, 0x3ff
	v_cmp_lt_i32_e32 vcc, s0, v72
	s_and_saveexec_b64 s[0:1], vcc
	s_xor_b64 s[16:17], exec, s[0:1]
	s_cbranch_execz .LBB0_179
	s_movk_i32 s0, 0x4ff
	v_cmp_lt_u32_e32 vcc, s0, v72
	s_and_saveexec_b64 s[0:1], vcc
	s_xor_b64 s[18:19], exec, s[0:1]
	s_cbranch_execz .LBB0_176
	s_movk_i32 s0, 0x73f
	v_cmp_lt_u32_e32 vcc, s0, v72
	s_and_saveexec_b64 s[0:1], vcc
	s_xor_b64 s[0:1], exec, s[0:1]
	s_cbranch_execz .LBB0_45
	v_add_u32_e32 v2, 0x300, v76
	s_waitcnt lgkmcnt(0)
	v_and_b32_e32 v14, 0x3c0, v2
	v_and_or_b32 v15, v74, s30, v1
	v_lshlrev_b32_e32 v2, 12, v14
	v_lshl_add_u64 v[4:5], s[40:41], 0, v[2:3]
	v_lshlrev_b32_e32 v2, 2, v15
	v_lshl_add_u64 v[32:33], v[4:5], 0, v[2:3]
	v_add_co_u32_e32 v4, vcc, s31, v32
	v_lshlrev_b32_e32 v2, 11, v15
	s_nop 0
	v_addc_co_u32_e32 v5, vcc, 0, v33, vcc
	v_add_co_u32_e32 v6, vcc, s33, v32
	s_nop 1
	v_addc_co_u32_e32 v7, vcc, 0, v33, vcc
	v_add_co_u32_e32 v8, vcc, s60, v32
	s_nop 1
	v_addc_co_u32_e32 v9, vcc, 0, v33, vcc
	v_add_co_u32_e32 v10, vcc, s61, v32
	s_nop 1
	v_addc_co_u32_e32 v11, vcc, 0, v33, vcc
	global_load_dword v16, v[32:33], off nt
	global_load_dword v17, v[4:5], off offset:-4096 nt
	global_load_dword v18, v[4:5], off nt
	global_load_dword v19, v[6:7], off offset:-4096 nt
	global_load_dword v20, v[6:7], off nt
	global_load_dword v21, v[8:9], off offset:-4096 nt
	global_load_dword v22, v[8:9], off nt
	global_load_dword v23, v[10:11], off offset:-4096 nt
	v_add_co_u32_e32 v4, vcc, s62, v32
	s_nop 1
	v_addc_co_u32_e32 v5, vcc, 0, v33, vcc
	v_add_co_u32_e32 v6, vcc, s63, v32
	s_nop 1
	v_addc_co_u32_e32 v7, vcc, 0, v33, vcc
	v_add_co_u32_e32 v8, vcc, s64, v32
	s_nop 1
	v_addc_co_u32_e32 v9, vcc, 0, v33, vcc
	v_add_co_u32_e32 v12, vcc, s65, v32
	s_nop 1
	v_addc_co_u32_e32 v13, vcc, 0, v33, vcc
	global_load_dword v24, v[10:11], off nt
	global_load_dword v25, v[4:5], off offset:-4096 nt
	global_load_dword v26, v[4:5], off nt
	global_load_dword v27, v[6:7], off offset:-4096 nt
	global_load_dword v28, v[6:7], off nt
	global_load_dword v29, v[8:9], off offset:-4096 nt
	global_load_dword v30, v[8:9], off nt
	global_load_dword v31, v[12:13], off offset:-4096 nt
	v_add_co_u32_e32 v4, vcc, s66, v32
	s_nop 1
	v_addc_co_u32_e32 v5, vcc, 0, v33, vcc
	v_add_co_u32_e32 v6, vcc, s67, v32
	s_nop 1
	v_addc_co_u32_e32 v7, vcc, 0, v33, vcc
	v_add_co_u32_e32 v8, vcc, s71, v32
	s_nop 1
	v_addc_co_u32_e32 v9, vcc, 0, v33, vcc
	v_add_co_u32_e32 v10, vcc, s72, v32
	s_nop 1
	v_addc_co_u32_e32 v11, vcc, 0, v33, vcc
	global_load_dword v12, v[12:13], off nt
	s_nop 0
	global_load_dword v13, v[4:5], off offset:-4096 nt
	global_load_dword v36, v[4:5], off nt
	global_load_dword v37, v[6:7], off offset:-4096 nt
	global_load_dword v38, v[6:7], off nt
	global_load_dword v39, v[8:9], off offset:-4096 nt
	global_load_dword v40, v[8:9], off nt
	global_load_dword v41, v[10:11], off offset:-4096 nt
	v_add_co_u32_e32 v4, vcc, s73, v32
	s_nop 1
	v_addc_co_u32_e32 v5, vcc, 0, v33, vcc
	v_add_co_u32_e32 v6, vcc, s74, v32
	s_nop 1
	v_addc_co_u32_e32 v7, vcc, 0, v33, vcc
	v_add_co_u32_e32 v8, vcc, s75, v32
	s_nop 1
	v_addc_co_u32_e32 v9, vcc, 0, v33, vcc
	v_add_co_u32_e32 v34, vcc, s76, v32
	s_nop 1
	v_addc_co_u32_e32 v35, vcc, 0, v33, vcc
	global_load_dword v10, v[10:11], off nt
	s_nop 0
	global_load_dword v11, v[4:5], off offset:-4096 nt
	global_load_dword v42, v[4:5], off nt
	global_load_dword v43, v[6:7], off offset:-4096 nt
	global_load_dword v44, v[6:7], off nt
	global_load_dword v45, v[8:9], off offset:-4096 nt
	global_load_dword v46, v[8:9], off nt
	global_load_dword v47, v[34:35], off offset:-4096 nt
	v_lshl_add_u64 v[4:5], s[28:29], 0, v[2:3]
	v_lshlrev_b32_e32 v2, 1, v14
	v_lshl_add_u64 v[4:5], v[4:5], 0, v[2:3]
	s_waitcnt vmcnt(30)
	v_cvt_pk_bf16_f32 v6, v16, v17
	s_waitcnt vmcnt(28)
	v_cvt_pk_bf16_f32 v7, v18, v19
	s_waitcnt vmcnt(26)
	v_cvt_pk_bf16_f32 v8, v20, v21
	s_waitcnt vmcnt(24)
	v_cvt_pk_bf16_f32 v9, v22, v23
	global_store_dwordx4 v[4:5], v[6:9], off
	s_waitcnt vmcnt(23)
	s_nop 0
	v_cvt_pk_bf16_f32 v6, v24, v25
	s_waitcnt vmcnt(21)
	v_cvt_pk_bf16_f32 v7, v26, v27
	s_waitcnt vmcnt(19)
	v_cvt_pk_bf16_f32 v8, v28, v29
	s_waitcnt vmcnt(17)
	v_cvt_pk_bf16_f32 v9, v30, v31
	global_store_dwordx4 v[4:5], v[6:9], off offset:16
	s_waitcnt vmcnt(16)
	s_nop 0
	v_cvt_pk_bf16_f32 v6, v12, v13
	s_waitcnt vmcnt(14)
	v_cvt_pk_bf16_f32 v7, v36, v37
	s_waitcnt vmcnt(12)
	v_cvt_pk_bf16_f32 v8, v38, v39
	v_add_co_u32_e32 v38, vcc, s77, v32
	s_waitcnt vmcnt(10)
	v_cvt_pk_bf16_f32 v9, v40, v41
	v_addc_co_u32_e32 v39, vcc, 0, v33, vcc
	v_add_co_u32_e32 v40, vcc, s78, v32
	global_store_dwordx4 v[4:5], v[6:9], off offset:32
	s_nop 0
	v_addc_co_u32_e32 v41, vcc, 0, v33, vcc
	s_waitcnt vmcnt(9)
	v_cvt_pk_bf16_f32 v6, v10, v11
	s_waitcnt vmcnt(7)
	v_cvt_pk_bf16_f32 v7, v42, v43
	s_waitcnt vmcnt(5)
	v_cvt_pk_bf16_f32 v8, v44, v45
	s_waitcnt vmcnt(3)
; DI void p0_weight_tile(const float* W, bf16_t* Bt, int N, const float* g, bool permute, int t, int lane) {
;     ...
;     for (int hh = 0; hh < 2; ++hh) {
;         float v[32];
; #pragma unroll
;         for (int k = 0; k < 32; ++k) v[k] = src[(size_t)(32 * hh + k) * N];
	v_cvt_pk_bf16_f32 v9, v46, v47
	global_store_dwordx4 v[4:5], v[6:9], off offset:48
	s_nop 1
	v_add_co_u32_e32 v6, vcc, s79, v32
	s_nop 1
	v_addc_co_u32_e32 v7, vcc, 0, v33, vcc
	v_add_co_u32_e32 v8, vcc, s80, v32
	s_nop 1
	v_addc_co_u32_e32 v9, vcc, 0, v33, vcc
	v_add_co_u32_e32 v10, vcc, s81, v32
	s_nop 1
	v_addc_co_u32_e32 v11, vcc, 0, v33, vcc
	v_add_co_u32_e32 v12, vcc, s82, v32
	s_nop 1
	v_addc_co_u32_e32 v13, vcc, 0, v33, vcc
	global_load_dword v31, v[6:7], off offset:-4096 nt
	global_load_dword v28, v[6:7], off nt
	global_load_dword v29, v[8:9], off offset:-4096 nt
	global_load_dword v24, v[8:9], off nt
	global_load_dword v25, v[10:11], off offset:-4096 nt
	global_load_dword v20, v[10:11], off nt
	global_load_dword v21, v[12:13], off offset:-4096 nt
	global_load_dword v14, v[12:13], off nt
	v_add_co_u32_e32 v6, vcc, s83, v32
	s_nop 1
	v_addc_co_u32_e32 v7, vcc, 0, v33, vcc
	v_add_co_u32_e32 v8, vcc, s84, v32
	s_nop 1
	v_addc_co_u32_e32 v9, vcc, 0, v33, vcc
	v_add_co_u32_e32 v10, vcc, s85, v32
	s_nop 1
	v_addc_co_u32_e32 v11, vcc, 0, v33, vcc
	v_add_co_u32_e32 v16, vcc, s86, v32
	s_nop 1
	v_addc_co_u32_e32 v17, vcc, 0, v33, vcc
	global_load_dword v15, v[6:7], off offset:-4096 nt
	global_load_dword v26, v[6:7], off nt
	global_load_dword v27, v[8:9], off offset:-4096 nt
	global_load_dword v18, v[8:9], off nt
	global_load_dword v19, v[10:11], off offset:-4096 nt
	global_load_dword v12, v[10:11], off nt
	global_load_dword v13, v[16:17], off offset:-4096 nt
	s_nop 0
	global_load_dword v8, v[16:17], off nt
	v_add_co_u32_e32 v6, vcc, s87, v32
	s_nop 1
	v_addc_co_u32_e32 v7, vcc, 0, v33, vcc
	v_add_co_u32_e32 v10, vcc, s88, v32
	s_nop 1
	v_addc_co_u32_e32 v11, vcc, 0, v33, vcc
	v_add_co_u32_e32 v36, vcc, s89, v32
	s_nop 1
	v_addc_co_u32_e32 v37, vcc, 0, v33, vcc
	v_add_co_u32_e32 v42, vcc, s90, v32
	s_nop 1
	v_addc_co_u32_e32 v43, vcc, 0, v33, vcc
	global_load_dword v9, v[6:7], off offset:-4096 nt
	global_load_dword v22, v[6:7], off nt
	global_load_dword v23, v[10:11], off offset:-4096 nt
	global_load_dword v16, v[10:11], off nt
	global_load_dword v17, v[36:37], off offset:-4096 nt
	s_nop 0
	global_load_dword v10, v[36:37], off nt
	global_load_dword v11, v[42:43], off offset:-4096 nt
	global_load_dword v6, v[42:43], off nt
	v_add_co_u32_e32 v42, vcc, 0x3d000, v32
	s_nop 1
	v_addc_co_u32_e32 v43, vcc, 0, v33, vcc
	v_add_co_u32_e32 v44, vcc, 0x3e000, v32
	s_nop 1
	v_addc_co_u32_e32 v45, vcc, 0, v33, vcc
	v_add_co_u32_e32 v46, vcc, 0x3f000, v32
	s_nop 1
	v_addc_co_u32_e32 v47, vcc, 0, v33, vcc
	global_load_dword v36, v[34:35], off nt
	global_load_dword v37, v[38:39], off offset:-4096 nt
	s_nop 0
	global_load_dword v34, v[38:39], off nt
	global_load_dword v35, v[40:41], off offset:-4096 nt
	global_load_dword v30, v[40:41], off nt
	global_load_dword v7, v[42:43], off nt
	global_load_dword v32, v[44:45], off nt
	global_load_dword v33, v[46:47], off nt
; DI void p0_weight_tile(const float* W, bf16_t* Bt, int N, const float* g, bool permute, int t, int lane) {
;     const int ntn = N / 64, k0 = (t / ntn) * 64, n0 = (t % ntn) * 64;
;     const int nlog = n0 + lane;
;     const int c = permute ? ((nlog & ~255) | (((nlog >> 5) & 1) << 7) | (((nlog >> 6) & 3) << 5) | (nlog & 31)) : nlog;
;     const float* src = W + (size_t)k0 * N + nlog;
;     bf16_t* dst = Bt + (size_t)c * 1024 + k0;
; #pragma unroll
;     for (int hh = 0; hh < 2; ++hh) {
;         float v[32];
; #pragma unroll
;         for (int k = 0; k < 32; ++k) v[k] = src[(size_t)(32 * hh + k) * N];
; #pragma unroll
;         for (int k = 0; k < 32; ++k) v[k] *= (g ? g[k0 + 32 * hh + k] : 1.0f);
; DI void p0_prologue(const Params& P, LAS unsigned char* lds) {
;     ...
;             else if (t < T0 + T1 + T2) p0_weight_tile(P.w_in_odd, (bf16_t*)(ws + WS_BT2), N_IN1, P.norm_odd, true, t - T0 - T1, lane);
.LBB0_45:
	s_andn2_saveexec_b64 s[20:21], s[0:1]
	s_cbranch_execz .LBB0_175
	v_add_u16_e32 v2, 0xfb00, v72
	v_mul_u32_u24_e32 v4, 0xe38f, v2
	v_lshrrev_b32_e32 v50, 21, v4
	v_mul_lo_u16_e32 v4, 36, v50
	v_sub_u16_e32 v4, v2, v4
	s_waitcnt lgkmcnt(0)
	v_lshlrev_b32_e32 v5, 6, v4
	v_or_b32_e32 v2, v5, v1
	s_waitcnt vmcnt(2)
	v_mov_b64_e32 v[6:7], s[38:39]
	v_mad_u64_u32 v[6:7], s[0:1], v50, s91, v[6:7]
	v_lshlrev_b32_e32 v2, 2, v2
	v_lshl_add_u64 v[6:7], v[6:7], 0, v[2:3]
	v_add_co_u32_e32 v8, vcc, 0x2000, v6
	s_nop 1
	v_addc_co_u32_e32 v9, vcc, 0, v7, vcc
	v_add_co_u32_e32 v10, vcc, 0x4000, v6
	s_nop 1
	v_addc_co_u32_e32 v11, vcc, 0, v7, vcc
	v_add_co_u32_e32 v12, vcc, 0x6000, v6
	s_nop 1
	v_addc_co_u32_e32 v13, vcc, 0, v7, vcc
	v_add_co_u32_e32 v14, vcc, 0x9000, v6
	s_nop 1
	v_addc_co_u32_e32 v15, vcc, 0, v7, vcc
	v_add_co_u32_e32 v16, vcc, 0xb000, v6
	s_nop 1
	v_addc_co_u32_e32 v17, vcc, 0, v7, vcc
	v_add_co_u32_e32 v18, vcc, 0xd000, v6
	s_nop 1
	v_addc_co_u32_e32 v19, vcc, 0, v7, vcc
	v_add_co_u32_e32 v20, vcc, 0xf000, v6
	s_nop 1
	v_addc_co_u32_e32 v21, vcc, 0, v7, vcc
	global_load_dword v2, v[6:7], off nt
	s_nop 0
	global_load_dword v8, v[8:9], off offset:1024 nt
	s_nop 0
	global_load_dword v9, v[10:11], off offset:2048 nt
	s_nop 0
	global_load_dword v10, v[12:13], off offset:3072 nt
	global_load_dword v11, v[14:15], off nt
	s_nop 0
	global_load_dword v12, v[16:17], off offset:1024 nt
	global_load_dword v13, v[18:19], off offset:2048 nt
	global_load_dword v14, v[20:21], off offset:3072 nt
	v_add_co_u32_e32 v16, vcc, 0x12000, v6
	s_nop 1
	v_addc_co_u32_e32 v17, vcc, 0, v7, vcc
	v_add_co_u32_e32 v18, vcc, 0x14000, v6
	s_nop 1
	v_addc_co_u32_e32 v19, vcc, 0, v7, vcc
	v_add_co_u32_e32 v20, vcc, 0x16000, v6
	s_nop 1
	v_addc_co_u32_e32 v21, vcc, 0, v7, vcc
	v_add_co_u32_e32 v22, vcc, 0x18000, v6
	s_nop 1
	v_addc_co_u32_e32 v23, vcc, 0, v7, vcc
	v_add_co_u32_e32 v24, vcc, 0x1b000, v6
	s_nop 1
	v_addc_co_u32_e32 v25, vcc, 0, v7, vcc
	v_add_co_u32_e32 v26, vcc, 0x1d000, v6
	s_nop 1
	v_addc_co_u32_e32 v27, vcc, 0, v7, vcc
	v_add_co_u32_e32 v28, vcc, 0x1f000, v6
	s_nop 1
	v_addc_co_u32_e32 v29, vcc, 0, v7, vcc
	v_add_co_u32_e32 v30, vcc, 0x21000, v6
	s_nop 1
	v_addc_co_u32_e32 v31, vcc, 0, v7, vcc
	global_load_dword v15, v[16:17], off nt
	s_nop 0
	global_load_dword v16, v[18:19], off offset:1024 nt
	global_load_dword v17, v[20:21], off offset:2048 nt
	s_nop 0
	global_load_dword v18, v[22:23], off offset:3072 nt
	global_load_dword v19, v[24:25], off nt
	global_load_dword v20, v[26:27], off offset:1024 nt
	global_load_dword v21, v[28:29], off offset:2048 nt
	s_nop 0
	global_load_dword v22, v[30:31], off offset:3072 nt
	v_add_co_u32_e32 v24, vcc, 0x24000, v6
	s_nop 1
	v_addc_co_u32_e32 v25, vcc, 0, v7, vcc
	v_add_co_u32_e32 v26, vcc, 0x26000, v6
	s_nop 1
	v_addc_co_u32_e32 v27, vcc, 0, v7, vcc
	v_add_co_u32_e32 v28, vcc, 0x28000, v6
	s_nop 1
	v_addc_co_u32_e32 v29, vcc, 0, v7, vcc
	v_add_co_u32_e32 v30, vcc, 0x2a000, v6
	s_nop 1
	v_addc_co_u32_e32 v31, vcc, 0, v7, vcc
	s_waitcnt vmcnt(17)
	v_add_co_u32_e32 v32, vcc, 0x2d000, v6
	s_waitcnt vmcnt(16)
	s_nop 0
	v_addc_co_u32_e32 v33, vcc, 0, v7, vcc
	v_add_co_u32_e32 v34, vcc, 0x2f000, v6
	s_nop 1
	v_addc_co_u32_e32 v35, vcc, 0, v7, vcc
	v_add_co_u32_e32 v36, vcc, 0x31000, v6
	s_nop 1
	v_addc_co_u32_e32 v37, vcc, 0, v7, vcc
	v_add_co_u32_e32 v38, vcc, 0x33000, v6
	s_nop 1
	v_addc_co_u32_e32 v39, vcc, 0, v7, vcc
	global_load_dword v23, v[24:25], off nt
	s_nop 0
	global_load_dword v24, v[26:27], off offset:1024 nt
	global_load_dword v25, v[28:29], off offset:2048 nt
	s_nop 0
	global_load_dword v26, v[30:31], off offset:3072 nt
	global_load_dword v27, v[32:33], off nt
	global_load_dword v28, v[34:35], off offset:1024 nt
	global_load_dword v29, v[36:37], off offset:2048 nt
	s_nop 0
	global_load_dword v30, v[38:39], off offset:3072 nt
	v_add_co_u32_e32 v32, vcc, 0x36000, v6
	v_cndmask_b32_e64 v34, 0, 1, s[10:11]
	s_nop 0
	v_addc_co_u32_e32 v33, vcc, 0, v7, vcc
	v_add_co_u32_e32 v36, vcc, 0x38000, v6
	v_cmp_ne_u32_e64 s[0:1], 1, v34
	s_nop 0
	v_addc_co_u32_e32 v37, vcc, 0, v7, vcc
	v_add_co_u32_e32 v38, vcc, 0x3a000, v6
	v_mov_b32_e32 v34, 1.0
	s_nop 0
	v_addc_co_u32_e32 v39, vcc, 0, v7, vcc
	v_add_co_u32_e32 v40, vcc, 0x3c000, v6
	s_nop 1
	v_addc_co_u32_e32 v41, vcc, 0, v7, vcc
	v_add_co_u32_e32 v42, vcc, 0x3f000, v6
	s_nop 1
	v_addc_co_u32_e32 v43, vcc, 0, v7, vcc
	v_add_co_u32_e32 v44, vcc, 0x41000, v6
	s_nop 1
	v_addc_co_u32_e32 v45, vcc, 0, v7, vcc
	v_add_co_u32_e32 v46, vcc, 0x43000, v6
	s_nop 1
	v_addc_co_u32_e32 v47, vcc, 0, v7, vcc
	v_add_co_u32_e32 v48, vcc, 0x45000, v6
	s_nop 1
	v_addc_co_u32_e32 v49, vcc, 0, v7, vcc
	global_load_dword v35, v[32:33], off nt
	s_nop 0
	global_load_dword v36, v[36:37], off offset:1024 nt
	s_nop 0
	global_load_dword v37, v[38:39], off offset:2048 nt
	s_nop 0
	global_load_dword v38, v[40:41], off offset:3072 nt
	global_load_dword v39, v[42:43], off nt
	s_nop 0
	global_load_dword v40, v[44:45], off offset:1024 nt
	global_load_dword v41, v[46:47], off offset:2048 nt
	global_load_dword v31, v[48:49], off offset:3072 nt
	v_lshlrev_b32_e32 v32, 6, v50
	v_mov_b32_e32 v33, 1.0
	s_andn2_b64 vcc, exec, s[10:11]
	v_lshlrev_b32_e32 v70, 2, v32
	s_cbranch_vccnz .LBB0_48
	global_load_dword v34, v70, s[36:37]

; DI unsigned cvt_pk(float lo, float hi) { const f32x2 v = {lo, hi}; return __builtin_bit_cast(unsigned, __builtin_convertvector(v, bf16v2)); }
; DI void p0_weight_tile(const float* W, bf16_t* Bt, int N, const float* g, bool permute, int t, int lane) {
;     ...
;     const int c = permute ? ((nlog & ~255) | (((nlog >> 5) & 1) << 7) | (((nlog >> 6) & 3) << 5) | (nlog & 31)) : nlog;
;     const float* src = W + (size_t)k0 * N + nlog;
;     bf16_t* dst = Bt + (size_t)c * 1024 + k0;
; #pragma unroll
;     for (int hh = 0; hh < 2; ++hh) {
;         float v[32];
; #pragma unroll
;         for (int k = 0; k < 32; ++k) v[k] = src[(size_t)(32 * hh + k) * N];
; #pragma unroll
;         for (int k = 0; k < 32; ++k) v[k] *= (g ? g[k0 + 32 * hh + k] : 1.0f);
; #pragma unroll
;         for (int j = 0; j < 4; ++j) {
;             u32x4 w; w.x = cvt_pk(v[8 * j], v[8 * j + 1]); w.y = cvt_pk(v[8 * j + 2], v[8 * j + 3]); w.z = cvt_pk(v[8 * j + 4], v[8 * j + 5]); w.w = cvt_pk(v[8 * j + 6], v[8 * j + 7]);
;             *(u32x4*)(dst + 32 * hh + 8 * j) = w;
;         }
.LBB0_110:
	v_lshlrev_b32_e32 v4, 5, v4
	s_waitcnt vmcnt(0)
	v_mul_f32_e32 v8, v8, v33
	v_mul_f32_e32 v33, v2, v34
	v_and_b32_e32 v2, 0xf00, v5
	v_and_b32_e32 v4, 0x60, v4
	v_or3_b32 v2, v2, v4, v73
	v_lshlrev_b32_e32 v2, 11, v2
	v_mul_f32_e32 v14, v14, v46
	v_mul_f32_e32 v13, v13, v47
	v_mul_f32_e32 v12, v12, v44
	v_mul_f32_e32 v11, v11, v45
	v_mul_f32_e32 v10, v10, v42
	v_mul_f32_e32 v9, v9, v43
	v_lshl_add_u64 v[4:5], s[42:43], 0, v[2:3]
	v_lshlrev_b32_e32 v2, 1, v32
	v_mul_f32_e32 v22, v22, v54
	v_mul_f32_e32 v21, v21, v55
	v_mul_f32_e32 v20, v20, v52
	v_mul_f32_e32 v19, v19, v53
	v_mul_f32_e32 v18, v18, v50
	v_mul_f32_e32 v17, v17, v51
	v_mul_f32_e32 v16, v16, v48
	v_mul_f32_e32 v15, v15, v49
	v_lshl_add_u64 v[4:5], v[4:5], 0, v[2:3]
	v_cvt_pk_bf16_f32 v8, v33, v8
	v_cvt_pk_bf16_f32 v9, v9, v10
	v_cvt_pk_bf16_f32 v10, v11, v12
	v_cvt_pk_bf16_f32 v11, v13, v14
	v_mul_f32_e32 v30, v30, v62
	v_mul_f32_e32 v29, v29, v63
	v_mul_f32_e32 v28, v28, v60
	v_mul_f32_e32 v27, v27, v61
	v_mul_f32_e32 v26, v26, v58
	v_mul_f32_e32 v25, v25, v59
	v_mul_f32_e32 v24, v24, v56
	v_mul_f32_e32 v23, v23, v57
	global_store_dwordx4 v[4:5], v[8:11], off
	v_mul_f32_e32 v41, v41, v77
	v_mul_f32_e32 v40, v40, v69
	v_cvt_pk_bf16_f32 v8, v15, v16
	v_cvt_pk_bf16_f32 v9, v17, v18
	v_cvt_pk_bf16_f32 v10, v19, v20
	v_cvt_pk_bf16_f32 v11, v21, v22
	v_mul_f32_e32 v39, v39, v71
	v_mul_f32_e32 v38, v38, v67
	v_mul_f32_e32 v37, v37, v68
	v_mul_f32_e32 v36, v36, v64
	v_mul_f32_e32 v35, v35, v65
	v_mul_f32_e32 v2, v31, v66
	global_store_dwordx4 v[4:5], v[8:11], off offset:16
	s_mov_b32 s45, 0x4a000
	s_nop 0
	v_cvt_pk_bf16_f32 v8, v23, v24
	v_cvt_pk_bf16_f32 v9, v25, v26
	v_cvt_pk_bf16_f32 v10, v27, v28
	v_cvt_pk_bf16_f32 v11, v29, v30
	global_store_dwordx4 v[4:5], v[8:11], off offset:32
	s_nop 1
	v_cvt_pk_bf16_f32 v8, v35, v36
	v_cvt_pk_bf16_f32 v9, v37, v38
	v_cvt_pk_bf16_f32 v10, v39, v40
	v_cvt_pk_bf16_f32 v11, v41, v2
	global_store_dwordx4 v[4:5], v[8:11], off offset:48
	s_nop 1
	v_add_co_u32_e32 v8, vcc, s92, v6
	s_nop 1
	v_addc_co_u32_e32 v9, vcc, 0, v7, vcc
	v_add_co_u32_e32 v10, vcc, s45, v6
	s_mov_b32 s45, 0x4e000
	s_nop 0
	v_addc_co_u32_e32 v11, vcc, 0, v7, vcc
	v_add_co_u32_e32 v12, vcc, s93, v6
	s_nop 1
	v_addc_co_u32_e32 v13, vcc, 0, v7, vcc
	v_add_co_u32_e32 v14, vcc, s45, v6
	s_mov_b32 s45, 0x51000
	s_nop 0
	v_addc_co_u32_e32 v15, vcc, 0, v7, vcc
	v_add_co_u32_e32 v16, vcc, s45, v6
	s_mov_b32 s45, 0x53000
	s_nop 0
	v_addc_co_u32_e32 v17, vcc, 0, v7, vcc
	v_add_co_u32_e32 v18, vcc, s45, v6
	s_mov_b32 s45, 0x55000
	s_nop 0
	v_addc_co_u32_e32 v19, vcc, 0, v7, vcc
	v_add_co_u32_e32 v20, vcc, s45, v6
	s_mov_b32 s45, 0x57000
	s_nop 0
	v_addc_co_u32_e32 v21, vcc, 0, v7, vcc
	v_add_co_u32_e32 v22, vcc, s45, v6
	s_mov_b32 s45, 0x5a000
	s_nop 0
	v_addc_co_u32_e32 v23, vcc, 0, v7, vcc
	global_load_dword v32, v[8:9], off nt
	global_load_dword v33, v[10:11], off offset:1024 nt
	global_load_dword v34, v[12:13], off offset:2048 nt
	global_load_dword v35, v[14:15], off offset:3072 nt
	global_load_dword v30, v[16:17], off nt
	global_load_dword v31, v[18:19], off offset:1024 nt
	global_load_dword v28, v[20:21], off offset:2048 nt
	global_load_dword v29, v[22:23], off offset:3072 nt
	v_add_co_u32_e32 v8, vcc, s45, v6
	s_mov_b32 s45, 0x5e000
	s_nop 0
	v_addc_co_u32_e32 v9, vcc, 0, v7, vcc
	v_add_co_u32_e32 v10, vcc, s95, v6
	s_nop 1
	v_addc_co_u32_e32 v11, vcc, 0, v7, vcc
	v_add_co_u32_e32 v12, vcc, s45, v6
	s_mov_b32 s45, 0x63000
	s_nop 0
	v_addc_co_u32_e32 v13, vcc, 0, v7, vcc
	v_add_co_u32_e32 v14, vcc, s96, v6
	s_nop 1
	v_addc_co_u32_e32 v15, vcc, 0, v7, vcc
	v_add_co_u32_e32 v16, vcc, s45, v6
	s_mov_b32 s45, 0x65000
	s_nop 0
	v_addc_co_u32_e32 v17, vcc, 0, v7, vcc
	v_add_co_u32_e32 v18, vcc, s45, v6
	s_mov_b32 s45, 0x67000
	s_nop 0
	v_addc_co_u32_e32 v19, vcc, 0, v7, vcc
	v_add_co_u32_e32 v22, vcc, s45, v6
	s_mov_b32 s45, 0x69000
	s_nop 0
	v_addc_co_u32_e32 v23, vcc, 0, v7, vcc
	v_add_co_u32_e32 v36, vcc, s45, v6
	s_mov_b32 s45, 0x6e000
	s_nop 0
	v_addc_co_u32_e32 v37, vcc, 0, v7, vcc
	global_load_dword v24, v[8:9], off nt
	global_load_dword v25, v[10:11], off offset:1024 nt
	global_load_dword v20, v[12:13], off offset:2048 nt
	global_load_dword v21, v[14:15], off offset:3072 nt
	s_nop 0
	global_load_dword v14, v[16:17], off nt
	global_load_dword v15, v[18:19], off offset:1024 nt
	global_load_dword v26, v[22:23], off offset:2048 nt
	global_load_dword v27, v[36:37], off offset:3072 nt
	v_add_co_u32_e32 v8, vcc, s97, v6
	s_nop 1
	v_addc_co_u32_e32 v9, vcc, 0, v7, vcc
	v_add_co_u32_e32 v10, vcc, s45, v6
	s_mov_b32 s45, 0x72000
	s_nop 0
	v_addc_co_u32_e32 v11, vcc, 0, v7, vcc
	v_add_co_u32_e32 v12, vcc, s6, v6
	s_nop 1
	v_addc_co_u32_e32 v13, vcc, 0, v7, vcc
	v_add_co_u32_e32 v16, vcc, s45, v6
	s_mov_b32 s45, 0x75000
	s_nop 0
	v_addc_co_u32_e32 v17, vcc, 0, v7, vcc
	v_add_co_u32_e32 v22, vcc, s45, v6
	s_mov_b32 s45, 0x77000
	s_nop 0
	v_addc_co_u32_e32 v23, vcc, 0, v7, vcc
	v_add_co_u32_e32 v36, vcc, s45, v6
	s_mov_b32 s45, 0x79000
	s_nop 0
	v_addc_co_u32_e32 v37, vcc, 0, v7, vcc
	v_add_co_u32_e32 v38, vcc, s45, v6
	s_mov_b32 s45, 0x7b000
	s_nop 0
	v_addc_co_u32_e32 v39, vcc, 0, v7, vcc
	v_add_co_u32_e32 v40, vcc, s45, v6
	s_mov_b32 s45, 0x7e000
	s_nop 0
	v_addc_co_u32_e32 v41, vcc, 0, v7, vcc
	global_load_dword v18, v[8:9], off nt
	global_load_dword v19, v[10:11], off offset:1024 nt
	s_nop 0
	global_load_dword v12, v[12:13], off offset:2048 nt
	s_nop 0
	global_load_dword v13, v[16:17], off offset:3072 nt
	global_load_dword v8, v[22:23], off nt
	global_load_dword v9, v[36:37], off offset:1024 nt
	s_nop 0
	global_load_dword v22, v[38:39], off offset:2048 nt
	global_load_dword v23, v[40:41], off offset:3072 nt
	v_add_co_u32_e32 v10, vcc, s45, v6
	s_mov_b32 s45, 0x82000
	s_nop 0
	v_addc_co_u32_e32 v11, vcc, 0, v7, vcc
	v_add_co_u32_e32 v36, vcc, s7, v6
	s_nop 1
	v_addc_co_u32_e32 v37, vcc, 0, v7, vcc
	v_add_co_u32_e32 v38, vcc, s45, v6
	s_mov_b32 s45, 0x87000
	s_nop 0
	v_addc_co_u32_e32 v39, vcc, 0, v7, vcc
	v_add_co_u32_e32 v40, vcc, s44, v6
	s_nop 1
	v_addc_co_u32_e32 v41, vcc, 0, v7, vcc
	v_add_co_u32_e32 v42, vcc, s45, v6
	s_nop 1
	v_addc_co_u32_e32 v43, vcc, 0, v7, vcc
	v_add_co_u32_e32 v44, vcc, 0x89000, v6
	s_nop 1
	v_addc_co_u32_e32 v45, vcc, 0, v7, vcc
	v_add_co_u32_e32 v46, vcc, 0x8b000, v6
	s_nop 1
	v_addc_co_u32_e32 v47, vcc, 0, v7, vcc
	v_add_co_u32_e32 v48, vcc, 0x8d000, v6
	s_nop 1
	v_addc_co_u32_e32 v49, vcc, 0, v7, vcc
	global_load_dword v16, v[10:11], off nt
	global_load_dword v17, v[36:37], off offset:1024 nt
	s_nop 0
	global_load_dword v10, v[38:39], off offset:2048 nt
	global_load_dword v11, v[40:41], off offset:3072 nt
	global_load_dword v6, v[42:43], off nt
	global_load_dword v7, v[44:45], off offset:1024 nt
	s_nop 0
	global_load_dword v38, v[46:47], off offset:2048 nt
	global_load_dword v39, v[48:49], off offset:3072 nt
	v_mov_b32_e32 v37, 1.0
	s_and_b64 vcc, exec, s[0:1]
	v_mov_b32_e32 v36, 1.0
	s_cbranch_vccnz .LBB0_112
	global_load_dword v36, v70, s[36:37] offset:128

; DI unsigned cvt_pk(float lo, float hi) { const f32x2 v = {lo, hi}; return __builtin_bit_cast(unsigned, __builtin_convertvector(v, bf16v2)); }
; DI void p0_weight_tile(const float* W, bf16_t* Bt, int N, const float* g, bool permute, int t, int lane) {
;     const int ntn = N / 64, k0 = (t / ntn) * 64, n0 = (t % ntn) * 64;
;     const int nlog = n0 + lane;
;     const int c = permute ? ((nlog & ~255) | (((nlog >> 5) & 1) << 7) | (((nlog >> 6) & 3) << 5) | (nlog & 31)) : nlog;
;     const float* src = W + (size_t)k0 * N + nlog;
;     bf16_t* dst = Bt + (size_t)c * 1024 + k0;
; #pragma unroll
;     for (int hh = 0; hh < 2; ++hh) {
;         float v[32];
; #pragma unroll
;         for (int k = 0; k < 32; ++k) v[k] = src[(size_t)(32 * hh + k) * N];
; #pragma unroll
;         for (int k = 0; k < 32; ++k) v[k] *= (g ? g[k0 + 32 * hh + k] : 1.0f);
; #pragma unroll
;         for (int j = 0; j < 4; ++j) {
;             u32x4 w; w.x = cvt_pk(v[8 * j], v[8 * j + 1]); w.y = cvt_pk(v[8 * j + 2], v[8 * j + 3]); w.z = cvt_pk(v[8 * j + 4], v[8 * j + 5]); w.w = cvt_pk(v[8 * j + 6], v[8 * j + 7]);
;             *(u32x4*)(dst + 32 * hh + 8 * j) = w;
;         }
.LBB0_176:
	s_andn2_saveexec_b64 s[0:1], s[18:19]
	s_cbranch_execz .LBB0_178
	s_waitcnt vmcnt(24) lgkmcnt(0)
	v_and_b32_e32 v14, 0x3c0, v76
	s_waitcnt vmcnt(23)
	v_and_or_b32 v15, v74, s30, v1
	v_lshlrev_b32_e32 v2, 12, v14
	v_lshl_add_u64 v[4:5], s[58:59], 0, v[2:3]
	v_lshlrev_b32_e32 v2, 2, v15
	s_waitcnt vmcnt(0)
	v_lshl_add_u64 v[32:33], v[4:5], 0, v[2:3]
	v_add_co_u32_e32 v4, vcc, s31, v32
	v_lshlrev_b32_e32 v2, 11, v15
	s_nop 0
	v_addc_co_u32_e32 v5, vcc, 0, v33, vcc
	v_add_co_u32_e32 v6, vcc, s33, v32
	s_nop 1
	v_addc_co_u32_e32 v7, vcc, 0, v33, vcc
	v_add_co_u32_e32 v8, vcc, s60, v32
	s_nop 1
	v_addc_co_u32_e32 v9, vcc, 0, v33, vcc
	v_add_co_u32_e32 v10, vcc, s61, v32
	s_nop 1
	v_addc_co_u32_e32 v11, vcc, 0, v33, vcc
	global_load_dword v16, v[32:33], off nt
	global_load_dword v17, v[4:5], off offset:-4096 nt
	global_load_dword v18, v[4:5], off nt
	global_load_dword v19, v[6:7], off offset:-4096 nt
	global_load_dword v20, v[6:7], off nt
	global_load_dword v21, v[8:9], off offset:-4096 nt
	global_load_dword v22, v[8:9], off nt
	global_load_dword v23, v[10:11], off offset:-4096 nt
	v_add_co_u32_e32 v4, vcc, s62, v32
	s_nop 1
	v_addc_co_u32_e32 v5, vcc, 0, v33, vcc
	v_add_co_u32_e32 v6, vcc, s63, v32
	s_nop 1
	v_addc_co_u32_e32 v7, vcc, 0, v33, vcc
	v_add_co_u32_e32 v8, vcc, s64, v32
	s_nop 1
	v_addc_co_u32_e32 v9, vcc, 0, v33, vcc
	v_add_co_u32_e32 v12, vcc, s65, v32
	s_nop 1
	v_addc_co_u32_e32 v13, vcc, 0, v33, vcc
	global_load_dword v24, v[10:11], off nt
	global_load_dword v25, v[4:5], off offset:-4096 nt
	global_load_dword v26, v[4:5], off nt
	global_load_dword v27, v[6:7], off offset:-4096 nt
	global_load_dword v28, v[6:7], off nt
	global_load_dword v29, v[8:9], off offset:-4096 nt
	global_load_dword v30, v[8:9], off nt
	global_load_dword v31, v[12:13], off offset:-4096 nt
	v_add_co_u32_e32 v4, vcc, s66, v32
	s_nop 1
	v_addc_co_u32_e32 v5, vcc, 0, v33, vcc
	v_add_co_u32_e32 v6, vcc, s67, v32
	s_nop 1
	v_addc_co_u32_e32 v7, vcc, 0, v33, vcc
	v_add_co_u32_e32 v8, vcc, s71, v32
	s_nop 1
	v_addc_co_u32_e32 v9, vcc, 0, v33, vcc
	v_add_co_u32_e32 v10, vcc, s72, v32
	s_nop 1
	v_addc_co_u32_e32 v11, vcc, 0, v33, vcc
	global_load_dword v12, v[12:13], off nt
	s_nop 0
	global_load_dword v13, v[4:5], off offset:-4096 nt
	global_load_dword v36, v[4:5], off nt
	global_load_dword v37, v[6:7], off offset:-4096 nt
	global_load_dword v38, v[6:7], off nt
	global_load_dword v39, v[8:9], off offset:-4096 nt
	global_load_dword v40, v[8:9], off nt
	global_load_dword v41, v[10:11], off offset:-4096 nt
	v_add_co_u32_e32 v4, vcc, s73, v32
	s_nop 1
	v_addc_co_u32_e32 v5, vcc, 0, v33, vcc
	v_add_co_u32_e32 v6, vcc, s74, v32
	s_nop 1
	v_addc_co_u32_e32 v7, vcc, 0, v33, vcc
	v_add_co_u32_e32 v8, vcc, s75, v32
	s_nop 1
	v_addc_co_u32_e32 v9, vcc, 0, v33, vcc
	v_add_co_u32_e32 v34, vcc, s76, v32
	s_nop 1
	v_addc_co_u32_e32 v35, vcc, 0, v33, vcc
	global_load_dword v10, v[10:11], off nt
	s_nop 0
	global_load_dword v11, v[4:5], off offset:-4096 nt
	global_load_dword v42, v[4:5], off nt
	global_load_dword v43, v[6:7], off offset:-4096 nt
	global_load_dword v44, v[6:7], off nt
	global_load_dword v45, v[8:9], off offset:-4096 nt
	global_load_dword v46, v[8:9], off nt
	global_load_dword v47, v[34:35], off offset:-4096 nt
	v_lshl_add_u64 v[4:5], s[46:47], 0, v[2:3]
	v_lshlrev_b32_e32 v2, 1, v14
	v_lshl_add_u64 v[4:5], v[4:5], 0, v[2:3]
	s_waitcnt vmcnt(30)
	v_cvt_pk_bf16_f32 v6, v16, v17
	s_waitcnt vmcnt(28)
	v_cvt_pk_bf16_f32 v7, v18, v19
	s_waitcnt vmcnt(26)
	v_cvt_pk_bf16_f32 v8, v20, v21
	s_waitcnt vmcnt(24)
	v_cvt_pk_bf16_f32 v9, v22, v23
	global_store_dwordx4 v[4:5], v[6:9], off
	s_waitcnt vmcnt(23)
	s_nop 0
	v_cvt_pk_bf16_f32 v6, v24, v25
	s_waitcnt vmcnt(21)
; DI unsigned cvt_pk(float lo, float hi) { const f32x2 v = {lo, hi}; return __builtin_bit_cast(unsigned, __builtin_convertvector(v, bf16v2)); }
; DI void p0_weight_tile(const float* W, bf16_t* Bt, int N, const float* g, bool permute, int t, int lane) {
;     ...
;     for (int hh = 0; hh < 2; ++hh) {
;         float v[32];
; #pragma unroll
;         for (int k = 0; k < 32; ++k) v[k] = src[(size_t)(32 * hh + k) * N];
; #pragma unroll
;         for (int k = 0; k < 32; ++k) v[k] *= (g ? g[k0 + 32 * hh + k] : 1.0f);
; #pragma unroll
;         for (int j = 0; j < 4; ++j) {
;             u32x4 w; w.x = cvt_pk(v[8 * j], v[8 * j + 1]); w.y = cvt_pk(v[8 * j + 2], v[8 * j + 3]); w.z = cvt_pk(v[8 * j + 4], v[8 * j + 5]); w.w = cvt_pk(v[8 * j + 6], v[8 * j + 7]);
;             *(u32x4*)(dst + 32 * hh + 8 * j) = w;
;         }
	v_cvt_pk_bf16_f32 v7, v26, v27
	s_waitcnt vmcnt(19)
	v_cvt_pk_bf16_f32 v8, v28, v29
	s_waitcnt vmcnt(17)
	v_cvt_pk_bf16_f32 v9, v30, v31
	global_store_dwordx4 v[4:5], v[6:9], off offset:16
	s_waitcnt vmcnt(16)
	s_nop 0
	v_cvt_pk_bf16_f32 v6, v12, v13
	s_waitcnt vmcnt(14)
	v_cvt_pk_bf16_f32 v7, v36, v37
	s_waitcnt vmcnt(12)
	v_cvt_pk_bf16_f32 v8, v38, v39
	v_add_co_u32_e32 v38, vcc, s77, v32
	s_waitcnt vmcnt(10)
	v_cvt_pk_bf16_f32 v9, v40, v41
	v_addc_co_u32_e32 v39, vcc, 0, v33, vcc
	v_add_co_u32_e32 v40, vcc, s78, v32
	global_store_dwordx4 v[4:5], v[6:9], off offset:32
	s_nop 0
	v_addc_co_u32_e32 v41, vcc, 0, v33, vcc
	s_waitcnt vmcnt(9)
	v_cvt_pk_bf16_f32 v6, v10, v11
	s_waitcnt vmcnt(7)
	v_cvt_pk_bf16_f32 v7, v42, v43
	s_waitcnt vmcnt(5)
	v_cvt_pk_bf16_f32 v8, v44, v45
	s_waitcnt vmcnt(3)
	v_cvt_pk_bf16_f32 v9, v46, v47
	global_store_dwordx4 v[4:5], v[6:9], off offset:48
	s_nop 1
	v_add_co_u32_e32 v6, vcc, s79, v32
	s_nop 1
	v_addc_co_u32_e32 v7, vcc, 0, v33, vcc
	v_add_co_u32_e32 v8, vcc, s80, v32
	s_nop 1
	v_addc_co_u32_e32 v9, vcc, 0, v33, vcc
	v_add_co_u32_e32 v10, vcc, s81, v32
	s_nop 1
	v_addc_co_u32_e32 v11, vcc, 0, v33, vcc
	v_add_co_u32_e32 v12, vcc, s82, v32
	s_nop 1
	v_addc_co_u32_e32 v13, vcc, 0, v33, vcc
	global_load_dword v31, v[6:7], off offset:-4096 nt
	global_load_dword v28, v[6:7], off nt
	global_load_dword v29, v[8:9], off offset:-4096 nt
	global_load_dword v24, v[8:9], off nt
	global_load_dword v25, v[10:11], off offset:-4096 nt
	global_load_dword v20, v[10:11], off nt
	global_load_dword v21, v[12:13], off offset:-4096 nt
	global_load_dword v14, v[12:13], off nt
	v_add_co_u32_e32 v6, vcc, s83, v32
	s_nop 1
	v_addc_co_u32_e32 v7, vcc, 0, v33, vcc
	v_add_co_u32_e32 v8, vcc, s84, v32
	s_nop 1
	v_addc_co_u32_e32 v9, vcc, 0, v33, vcc
	v_add_co_u32_e32 v10, vcc, s85, v32
	s_nop 1
	v_addc_co_u32_e32 v11, vcc, 0, v33, vcc
	v_add_co_u32_e32 v16, vcc, s86, v32
	s_nop 1
	v_addc_co_u32_e32 v17, vcc, 0, v33, vcc
	global_load_dword v15, v[6:7], off offset:-4096 nt
	global_load_dword v26, v[6:7], off nt
	global_load_dword v27, v[8:9], off offset:-4096 nt
	global_load_dword v18, v[8:9], off nt
	global_load_dword v19, v[10:11], off offset:-4096 nt
	global_load_dword v12, v[10:11], off nt
	global_load_dword v13, v[16:17], off offset:-4096 nt
	s_nop 0
	global_load_dword v8, v[16:17], off nt
	v_add_co_u32_e32 v6, vcc, s87, v32
	s_nop 1
	v_addc_co_u32_e32 v7, vcc, 0, v33, vcc
	v_add_co_u32_e32 v10, vcc, s88, v32
	s_nop 1
	v_addc_co_u32_e32 v11, vcc, 0, v33, vcc
	v_add_co_u32_e32 v36, vcc, s89, v32
	s_nop 1
	v_addc_co_u32_e32 v37, vcc, 0, v33, vcc
	v_add_co_u32_e32 v42, vcc, s90, v32
	s_nop 1
	v_addc_co_u32_e32 v43, vcc, 0, v33, vcc
	global_load_dword v9, v[6:7], off offset:-4096 nt
	global_load_dword v22, v[6:7], off nt
	global_load_dword v23, v[10:11], off offset:-4096 nt
	global_load_dword v16, v[10:11], off nt
	global_load_dword v17, v[36:37], off offset:-4096 nt
	s_nop 0
	global_load_dword v10, v[36:37], off nt
	global_load_dword v11, v[42:43], off offset:-4096 nt
	global_load_dword v6, v[42:43], off nt
	v_add_co_u32_e32 v42, vcc, 0x3d000, v32
	s_nop 1
	v_addc_co_u32_e32 v43, vcc, 0, v33, vcc
	v_add_co_u32_e32 v44, vcc, 0x3e000, v32
	s_nop 1
	v_addc_co_u32_e32 v45, vcc, 0, v33, vcc
	v_add_co_u32_e32 v46, vcc, 0x3f000, v32
	s_nop 1
	v_addc_co_u32_e32 v47, vcc, 0, v33, vcc
	global_load_dword v36, v[34:35], off nt
	global_load_dword v37, v[38:39], off offset:-4096 nt
	s_nop 0
	global_load_dword v34, v[38:39], off nt
	global_load_dword v35, v[40:41], off offset:-4096 nt
	global_load_dword v30, v[40:41], off nt
	global_load_dword v7, v[42:43], off nt
	global_load_dword v32, v[44:45], off nt
	global_load_dword v33, v[46:47], off nt

; DI void p0_weight_tile(const float* W, bf16_t* Bt, int N, const float* g, bool permute, int t, int lane) {
;     const int ntn = N / 64, k0 = (t / ntn) * 64, n0 = (t % ntn) * 64;
;     const int nlog = n0 + lane;
;     const int c = permute ? ((nlog & ~255) | (((nlog >> 5) & 1) << 7) | (((nlog >> 6) & 3) << 5) | (nlog & 31)) : nlog;
;     const float* src = W + (size_t)k0 * N + nlog;
;     bf16_t* dst = Bt + (size_t)c * 1024 + k0;
; #pragma unroll
;     for (int hh = 0; hh < 2; ++hh) {
;         float v[32];
; #pragma unroll
;         for (int k = 0; k < 32; ++k) v[k] = src[(size_t)(32 * hh + k) * N];
; #pragma unroll
;         for (int k = 0; k < 32; ++k) v[k] *= (g ? g[k0 + 32 * hh + k] : 1.0f);
.LBB0_179:
	s_andn2_saveexec_b64 s[16:17], s[16:17]
	s_cbranch_execz .LBB0_40
	v_ashrrev_i32_e32 v2, 31, v72
	v_lshrrev_b32_e32 v2, 26, v2
	v_add_u32_e32 v2, v72, v2
	s_waitcnt lgkmcnt(0)
	v_ashrrev_i32_e32 v5, 6, v2
	v_and_b32_e32 v4, 0xffffffc0, v2
	v_lshlrev_b32_e32 v2, 12, v5
	v_add_u32_e32 v5, v1, v74
	s_waitcnt vmcnt(8)
	v_sub_u32_e32 v6, v5, v2
	v_ashrrev_i32_e32 v5, 31, v4
	v_lshlrev_b64 v[8:9], 14, v[4:5]
	v_lshl_add_u64 v[8:9], s[56:57], 0, v[8:9]
	s_waitcnt vmcnt(2)
	v_ashrrev_i32_e32 v7, 31, v6
	v_lshl_add_u64 v[8:9], v[6:7], 2, v[8:9]
	v_add_co_u32_e32 v6, vcc, s33, v8
	s_mov_b32 s0, 0x40000
	s_nop 0
	v_addc_co_u32_e32 v7, vcc, 0, v9, vcc
	v_add_co_u32_e32 v12, vcc, s61, v8
	s_nop 1
	v_addc_co_u32_e32 v13, vcc, 0, v9, vcc
	v_add_co_u32_e32 v14, vcc, s63, v8
	s_nop 1
	v_addc_co_u32_e32 v15, vcc, 0, v9, vcc
	v_add_co_u32_e32 v16, vcc, s65, v8
	s_nop 1
	v_addc_co_u32_e32 v17, vcc, 0, v9, vcc
	v_add_co_u32_e32 v18, vcc, s67, v8
	s_nop 1
	v_addc_co_u32_e32 v19, vcc, 0, v9, vcc
	v_add_co_u32_e32 v20, vcc, s72, v8
	s_nop 1
	v_addc_co_u32_e32 v21, vcc, 0, v9, vcc
	v_add_co_u32_e32 v22, vcc, s74, v8
	s_nop 1
	v_addc_co_u32_e32 v23, vcc, 0, v9, vcc
	global_load_dword v10, v[8:9], off nt
	global_load_dword v11, v[6:7], off nt
	s_nop 0
	global_load_dword v12, v[12:13], off nt
	s_nop 0
	global_load_dword v13, v[14:15], off nt
	s_nop 0
	global_load_dword v14, v[16:17], off nt
	global_load_dword v15, v[18:19], off nt
	s_nop 0
	global_load_dword v16, v[20:21], off nt
	global_load_dword v17, v[22:23], off nt
	v_add_co_u32_e32 v6, vcc, s76, v8
	s_nop 1
	v_addc_co_u32_e32 v7, vcc, 0, v9, vcc
	v_add_co_u32_e32 v20, vcc, s78, v8
	s_nop 1
	v_addc_co_u32_e32 v21, vcc, 0, v9, vcc
	v_add_co_u32_e32 v22, vcc, s80, v8
	s_nop 1
	v_addc_co_u32_e32 v23, vcc, 0, v9, vcc
	v_add_co_u32_e32 v24, vcc, s82, v8
	s_nop 1
	v_addc_co_u32_e32 v25, vcc, 0, v9, vcc
	v_add_co_u32_e32 v26, vcc, s84, v8
	s_nop 1
	v_addc_co_u32_e32 v27, vcc, 0, v9, vcc
	v_add_co_u32_e32 v28, vcc, s86, v8
	s_nop 1
	v_addc_co_u32_e32 v29, vcc, 0, v9, vcc
	v_add_co_u32_e32 v30, vcc, s88, v8
	s_nop 1
	v_addc_co_u32_e32 v31, vcc, 0, v9, vcc
	s_waitcnt vmcnt(9)
	v_add_co_u32_e32 v32, vcc, s90, v8
	s_waitcnt vmcnt(8)
	s_nop 0
	v_addc_co_u32_e32 v33, vcc, 0, v9, vcc
	global_load_dword v18, v[6:7], off nt
	global_load_dword v19, v[20:21], off nt
	s_nop 0
	global_load_dword v20, v[22:23], off nt
	global_load_dword v21, v[24:25], off nt
	s_nop 0
	global_load_dword v22, v[26:27], off nt
	global_load_dword v23, v[28:29], off nt
	global_load_dword v24, v[30:31], off nt
	global_load_dword v25, v[32:33], off nt
	v_add_co_u32_e32 v6, vcc, s0, v8
	s_mov_b32 s0, 0x44000
	s_nop 0
	v_addc_co_u32_e32 v7, vcc, 0, v9, vcc
	v_add_co_u32_e32 v28, vcc, s0, v8
	s_mov_b32 s0, 0x50000
	s_nop 0
	v_addc_co_u32_e32 v29, vcc, 0, v9, vcc
	v_add_co_u32_e32 v30, vcc, s92, v8
	s_nop 1
	v_addc_co_u32_e32 v31, vcc, 0, v9, vcc
	v_add_co_u32_e32 v32, vcc, s93, v8
	s_nop 1
	v_addc_co_u32_e32 v33, vcc, 0, v9, vcc
	v_add_co_u32_e32 v34, vcc, s0, v8
	s_mov_b32 s0, 0x54000
	s_nop 0
	v_addc_co_u32_e32 v35, vcc, 0, v9, vcc
	v_add_co_u32_e32 v36, vcc, s0, v8
	s_mov_b32 s0, 0x58000
	s_nop 0
	v_addc_co_u32_e32 v37, vcc, 0, v9, vcc
	v_add_co_u32_e32 v38, vcc, s0, v8
	s_mov_b32 s0, 0x64000
	s_nop 0
	v_addc_co_u32_e32 v39, vcc, 0, v9, vcc
	v_add_co_u32_e32 v40, vcc, s95, v8
	s_nop 1
	v_addc_co_u32_e32 v41, vcc, 0, v9, vcc
	global_load_dword v26, v[6:7], off nt
	global_load_dword v27, v[28:29], off nt
	s_nop 0
	global_load_dword v28, v[30:31], off nt
	global_load_dword v29, v[32:33], off nt
	s_nop 0
	global_load_dword v30, v[34:35], off nt
	global_load_dword v31, v[36:37], off nt
	global_load_dword v32, v[38:39], off nt
	global_load_dword v33, v[40:41], off nt
	v_add_co_u32_e32 v6, vcc, s96, v8
	v_mov_b32_e32 v36, 1.0
	s_nop 0
	v_addc_co_u32_e32 v7, vcc, 0, v9, vcc
	v_add_co_u32_e32 v34, vcc, s0, v8
	s_mov_b32 s0, 0x68000
	s_nop 0
	v_addc_co_u32_e32 v35, vcc, 0, v9, vcc
	v_add_co_u32_e32 v40, vcc, s0, v8
	s_nop 1
	v_addc_co_u32_e32 v41, vcc, 0, v9, vcc
	v_add_co_u32_e32 v42, vcc, s97, v8
	s_nop 1
	v_addc_co_u32_e32 v43, vcc, 0, v9, vcc
	v_add_co_u32_e32 v44, vcc, s6, v8
	s_nop 1
	v_addc_co_u32_e32 v45, vcc, 0, v9, vcc
	v_add_co_u32_e32 v46, vcc, 0x74000, v8
	s_nop 1
	v_addc_co_u32_e32 v47, vcc, 0, v9, vcc
	v_add_co_u32_e32 v48, vcc, 0x78000, v8
	s_nop 1
	v_addc_co_u32_e32 v49, vcc, 0, v9, vcc
	v_add_co_u32_e32 v50, vcc, 0x7c000, v8
	s_nop 1
	v_addc_co_u32_e32 v51, vcc, 0, v9, vcc
	global_load_dword v37, v[6:7], off nt
	global_load_dword v38, v[34:35], off nt
	global_load_dword v39, v[40:41], off nt
	s_nop 0
	global_load_dword v40, v[42:43], off nt
	global_load_dword v41, v[44:45], off nt
	s_nop 0
	global_load_dword v42, v[46:47], off nt
	global_load_dword v43, v[48:49], off nt
	global_load_dword v34, v[50:51], off nt
	v_cndmask_b32_e64 v6, 0, 1, s[12:13]
	v_mov_b32_e32 v35, 1.0
	v_cmp_ne_u32_e64 s[0:1], 1, v6
	s_andn2_b64 vcc, exec, s[12:13]
	v_lshl_add_u64 v[6:7], v[4:5], 2, s[54:55]
	s_cbranch_vccnz .LBB0_182
	global_load_dword v36, v[6:7], off nt
.LBB0_182:
	s_and_b64 vcc, exec, s[0:1]
	s_cbranch_vccnz .LBB0_184
	global_load_dword v35, v[6:7], off offset:4 nt
.LBB0_184:
	v_mov_b32_e32 v44, 1.0
	s_and_b64 vcc, exec, s[0:1]
	v_mov_b32_e32 v45, 1.0
	s_cbranch_vccnz .LBB0_186
	global_load_dword v45, v[6:7], off offset:8 nt
.LBB0_186:
	s_and_b64 vcc, exec, s[0:1]
	s_cbranch_vccnz .LBB0_188
	global_load_dword v44, v[6:7], off offset:12 nt
.LBB0_188:
	v_mov_b32_e32 v46, 1.0
	s_and_b64 vcc, exec, s[0:1]
	v_mov_b32_e32 v47, 1.0
	s_cbranch_vccnz .LBB0_190
	global_load_dword v47, v[6:7], off offset:16 nt
; DI unsigned cvt_pk(float lo, float hi) { const f32x2 v = {lo, hi}; return __builtin_bit_cast(unsigned, __builtin_convertvector(v, bf16v2)); }
; DI void p0_weight_tile(const float* W, bf16_t* Bt, int N, const float* g, bool permute, int t, int lane) {
;     ...
;         for (int k = 0; k < 32; ++k) v[k] = src[(size_t)(32 * hh + k) * N];
; #pragma unroll
;         for (int k = 0; k < 32; ++k) v[k] *= (g ? g[k0 + 32 * hh + k] : 1.0f);
; #pragma unroll
;         for (int j = 0; j < 4; ++j) {
;             u32x4 w; w.x = cvt_pk(v[8 * j], v[8 * j + 1]); w.y = cvt_pk(v[8 * j + 2], v[8 * j + 3]); w.z = cvt_pk(v[8 * j + 4], v[8 * j + 5]); w.w = cvt_pk(v[8 * j + 6], v[8 * j + 7]);
;             *(u32x4*)(dst + 32 * hh + 8 * j) = w;
;         }
.LBB0_190:
	s_and_b64 vcc, exec, s[0:1]
	s_cbranch_vccnz .LBB0_192
	global_load_dword v46, v[6:7], off offset:20 nt
.LBB0_192:
	v_mov_b32_e32 v48, 1.0
	s_and_b64 vcc, exec, s[0:1]
	v_mov_b32_e32 v49, 1.0
	s_cbranch_vccnz .LBB0_194
	global_load_dword v49, v[6:7], off offset:24 nt
.LBB0_194:
	s_and_b64 vcc, exec, s[0:1]
	s_cbranch_vccnz .LBB0_196
	global_load_dword v48, v[6:7], off offset:28 nt
.LBB0_196:
	v_mov_b32_e32 v50, 1.0
	s_and_b64 vcc, exec, s[0:1]
	v_mov_b32_e32 v51, 1.0
	s_cbranch_vccnz .LBB0_198
	global_load_dword v51, v[6:7], off offset:32 nt
.LBB0_198:
	s_and_b64 vcc, exec, s[0:1]
	s_cbranch_vccnz .LBB0_200
	global_load_dword v50, v[6:7], off offset:36 nt
.LBB0_200:
	v_mov_b32_e32 v52, 1.0
	s_and_b64 vcc, exec, s[0:1]
	v_mov_b32_e32 v53, 1.0
	s_cbranch_vccnz .LBB0_202
	global_load_dword v53, v[6:7], off offset:40 nt
.LBB0_202:
	s_and_b64 vcc, exec, s[0:1]
	s_cbranch_vccnz .LBB0_204
	global_load_dword v52, v[6:7], off offset:44 nt
.LBB0_204:
	v_mov_b32_e32 v54, 1.0
	s_and_b64 vcc, exec, s[0:1]
	v_mov_b32_e32 v55, 1.0
	s_cbranch_vccnz .LBB0_206
	global_load_dword v55, v[6:7], off offset:48 nt
.LBB0_206:
	s_and_b64 vcc, exec, s[0:1]
	s_cbranch_vccnz .LBB0_208
	global_load_dword v54, v[6:7], off offset:52 nt
.LBB0_208:
	v_mov_b32_e32 v56, 1.0
	s_and_b64 vcc, exec, s[0:1]
	v_mov_b32_e32 v57, 1.0
	s_cbranch_vccnz .LBB0_210
	global_load_dword v57, v[6:7], off offset:56 nt
.LBB0_210:
	s_and_b64 vcc, exec, s[0:1]
	s_cbranch_vccnz .LBB0_212
	global_load_dword v56, v[6:7], off offset:60 nt
.LBB0_212:
	v_mov_b32_e32 v58, 1.0
	s_and_b64 vcc, exec, s[0:1]
	v_mov_b32_e32 v59, 1.0
	s_cbranch_vccnz .LBB0_214
	global_load_dword v59, v[6:7], off offset:64 nt
.LBB0_214:
	s_and_b64 vcc, exec, s[0:1]
	s_cbranch_vccnz .LBB0_216
	global_load_dword v58, v[6:7], off offset:68 nt
.LBB0_216:
	v_mov_b32_e32 v60, 1.0
	s_and_b64 vcc, exec, s[0:1]
	v_mov_b32_e32 v61, 1.0
	s_cbranch_vccnz .LBB0_218
	global_load_dword v61, v[6:7], off offset:72 nt
.LBB0_218:
	s_and_b64 vcc, exec, s[0:1]
	s_cbranch_vccnz .LBB0_220
	global_load_dword v60, v[6:7], off offset:76 nt
.LBB0_220:
	v_mov_b32_e32 v62, 1.0
	s_and_b64 vcc, exec, s[0:1]
	v_mov_b32_e32 v63, 1.0
	s_cbranch_vccnz .LBB0_222
	global_load_dword v63, v[6:7], off offset:80 nt
.LBB0_222:
	s_and_b64 vcc, exec, s[0:1]
	s_cbranch_vccnz .LBB0_224
	global_load_dword v62, v[6:7], off offset:84 nt
.LBB0_224:
	v_mov_b32_e32 v64, 1.0
	s_and_b64 vcc, exec, s[0:1]
	v_mov_b32_e32 v65, 1.0
	s_cbranch_vccnz .LBB0_226
	global_load_dword v65, v[6:7], off offset:88 nt
.LBB0_226:
	s_and_b64 vcc, exec, s[0:1]
	s_cbranch_vccnz .LBB0_228
	global_load_dword v64, v[6:7], off offset:92 nt
.LBB0_228:
	v_mov_b32_e32 v66, 1.0
	s_and_b64 vcc, exec, s[0:1]
	v_mov_b32_e32 v67, 1.0
	s_cbranch_vccnz .LBB0_230
	global_load_dword v67, v[6:7], off offset:96 nt
.LBB0_230:
	s_and_b64 vcc, exec, s[0:1]
	s_cbranch_vccnz .LBB0_232
	global_load_dword v66, v[6:7], off offset:100 nt
.LBB0_232:
	v_mov_b32_e32 v69, 1.0
	s_and_b64 vcc, exec, s[0:1]
	v_mov_b32_e32 v70, 1.0
	s_cbranch_vccnz .LBB0_234
	global_load_dword v70, v[6:7], off offset:104 nt
.LBB0_234:
	s_and_b64 vcc, exec, s[0:1]
	s_cbranch_vccnz .LBB0_236
	global_load_dword v69, v[6:7], off offset:108 nt
.LBB0_236:
	v_mov_b32_e32 v71, 1.0
	s_and_b64 vcc, exec, s[0:1]
	v_mov_b32_e32 v77, 1.0
	s_cbranch_vccnz .LBB0_238
	global_load_dword v77, v[6:7], off offset:112 nt
.LBB0_238:
	s_and_b64 vcc, exec, s[0:1]
	s_cbranch_vccnz .LBB0_240
	global_load_dword v71, v[6:7], off offset:116 nt
.LBB0_240:
	v_mov_b32_e32 v68, 1.0
	s_and_b64 vcc, exec, s[0:1]
	v_mov_b32_e32 v78, 1.0
	s_cbranch_vccnz .LBB0_242
	global_load_dword v78, v[6:7], off offset:120 nt
.LBB0_242:
	s_and_b64 vcc, exec, s[0:1]
	s_cbranch_vccnz .LBB0_244
	global_load_dword v68, v[6:7], off offset:124 nt
.LBB0_244:
	v_sub_u32_e32 v2, 0, v2
	v_add_u32_e32 v2, v74, v2
	s_waitcnt vmcnt(0)
	v_mul_f32_e32 v36, v10, v36
	v_and_b32_e32 v2, 0xffffff00, v2
	v_and_b32_e32 v10, 0x60, v75
	v_or3_b32 v10, v10, v2, v73
	v_mul_f32_e32 v35, v11, v35
	v_ashrrev_i32_e32 v11, 31, v10
	v_lshlrev_b64 v[10:11], 11, v[10:11]
	v_mul_f32_e32 v17, v17, v48
	v_mul_f32_e32 v16, v16, v49
	v_mul_f32_e32 v15, v15, v46
	v_mul_f32_e32 v14, v14, v47
	v_mul_f32_e32 v13, v13, v44
	v_mul_f32_e32 v12, v12, v45
	v_lshl_add_u64 v[10:11], s[50:51], 0, v[10:11]
	v_mul_f32_e32 v25, v25, v56
	v_mul_f32_e32 v24, v24, v57
	v_mul_f32_e32 v23, v23, v54
	v_mul_f32_e32 v22, v22, v55
	v_mul_f32_e32 v21, v21, v52
	v_mul_f32_e32 v20, v20, v53
	v_mul_f32_e32 v19, v19, v50
	v_mul_f32_e32 v18, v18, v51
	v_lshl_add_u64 v[4:5], v[4:5], 1, v[10:11]
	v_cvt_pk_bf16_f32 v10, v36, v35
	v_cvt_pk_bf16_f32 v11, v12, v13
	v_cvt_pk_bf16_f32 v12, v14, v15
	v_cvt_pk_bf16_f32 v13, v16, v17
	v_mul_f32_e32 v33, v33, v64
	v_mul_f32_e32 v32, v32, v65
	v_mul_f32_e32 v31, v31, v62
	v_mul_f32_e32 v30, v30, v63
	v_mul_f32_e32 v29, v29, v60
	v_mul_f32_e32 v28, v28, v61
	v_mul_f32_e32 v27, v27, v58
	v_mul_f32_e32 v26, v26, v59
	global_store_dwordx4 v[4:5], v[10:13], off
	v_mul_f32_e32 v43, v43, v78
	v_mul_f32_e32 v42, v42, v71
	v_cvt_pk_bf16_f32 v10, v18, v19
	v_cvt_pk_bf16_f32 v11, v20, v21
	v_cvt_pk_bf16_f32 v12, v22, v23
	v_cvt_pk_bf16_f32 v13, v24, v25
	v_mul_f32_e32 v41, v41, v77
	v_mul_f32_e32 v40, v40, v69
	v_mul_f32_e32 v39, v39, v70
	v_mul_f32_e32 v38, v38, v66
	v_mul_f32_e32 v37, v37, v67
	v_mul_f32_e32 v2, v34, v68
	global_store_dwordx4 v[4:5], v[10:13], off offset:16
	s_mov_b32 s18, 0x88000
	s_nop 0
	v_cvt_pk_bf16_f32 v10, v26, v27
	v_cvt_pk_bf16_f32 v11, v28, v29
	v_cvt_pk_bf16_f32 v12, v30, v31
	v_cvt_pk_bf16_f32 v13, v32, v33
	global_store_dwordx4 v[4:5], v[10:13], off offset:32
	s_nop 1
	v_cvt_pk_bf16_f32 v10, v37, v38
; DI void p0_weight_tile(const float* W, bf16_t* Bt, int N, const float* g, bool permute, int t, int lane) {
;     ...
;     for (int hh = 0; hh < 2; ++hh) {
;         float v[32];
; #pragma unroll
;         for (int k = 0; k < 32; ++k) v[k] = src[(size_t)(32 * hh + k) * N];
; #pragma unroll
;         for (int k = 0; k < 32; ++k) v[k] *= (g ? g[k0 + 32 * hh + k] : 1.0f);
	v_cvt_pk_bf16_f32 v11, v39, v40
	v_cvt_pk_bf16_f32 v12, v41, v42
	v_cvt_pk_bf16_f32 v13, v43, v2
	global_store_dwordx4 v[4:5], v[10:13], off offset:48
	s_nop 1
	v_add_co_u32_e32 v10, vcc, s7, v8
	s_nop 1
	v_addc_co_u32_e32 v11, vcc, 0, v9, vcc
	v_add_co_u32_e32 v12, vcc, s44, v8
	s_nop 1
	v_addc_co_u32_e32 v13, vcc, 0, v9, vcc
	v_add_co_u32_e32 v14, vcc, s18, v8
	s_mov_b32 s18, 0x8c000
	s_nop 0
	v_addc_co_u32_e32 v15, vcc, 0, v9, vcc
	v_add_co_u32_e32 v16, vcc, s18, v8
	s_mov_b32 s18, 0x94000
	s_nop 0
	v_addc_co_u32_e32 v17, vcc, 0, v9, vcc
	v_add_co_u32_e32 v18, vcc, s91, v8
	s_nop 1
	v_addc_co_u32_e32 v19, vcc, 0, v9, vcc
	v_add_co_u32_e32 v20, vcc, s18, v8
	s_mov_b32 s18, 0x98000
	s_nop 0
	v_addc_co_u32_e32 v21, vcc, 0, v9, vcc
	v_add_co_u32_e32 v22, vcc, s18, v8
	s_mov_b32 s18, 0x9c000
	s_nop 0
	v_addc_co_u32_e32 v23, vcc, 0, v9, vcc
	v_add_co_u32_e32 v24, vcc, s18, v8
	s_mov_b32 s18, 0xa0000
	s_nop 0
	v_addc_co_u32_e32 v25, vcc, 0, v9, vcc
	global_load_dword v32, v[10:11], off nt
	global_load_dword v33, v[12:13], off nt
	global_load_dword v34, v[14:15], off nt
	global_load_dword v35, v[16:17], off nt
	global_load_dword v30, v[18:19], off nt
	global_load_dword v31, v[20:21], off nt
	global_load_dword v28, v[22:23], off nt
	global_load_dword v29, v[24:25], off nt
	v_add_co_u32_e32 v10, vcc, s18, v8
	s_mov_b32 s18, 0xa4000
	s_nop 0
	v_addc_co_u32_e32 v11, vcc, 0, v9, vcc
	v_add_co_u32_e32 v12, vcc, s18, v8
	s_mov_b32 s18, 0xa8000
	s_nop 0
	v_addc_co_u32_e32 v13, vcc, 0, v9, vcc
	v_add_co_u32_e32 v14, vcc, s18, v8
	s_mov_b32 s18, 0xac000
	s_nop 0
	v_addc_co_u32_e32 v15, vcc, 0, v9, vcc
	v_add_co_u32_e32 v16, vcc, s18, v8
	s_mov_b32 s18, 0xb0000
	s_nop 0
	v_addc_co_u32_e32 v17, vcc, 0, v9, vcc
	v_add_co_u32_e32 v18, vcc, s18, v8
	s_mov_b32 s18, 0xb4000
	s_nop 0
	v_addc_co_u32_e32 v19, vcc, 0, v9, vcc
	v_add_co_u32_e32 v22, vcc, s18, v8
	s_mov_b32 s18, 0xb8000
	s_nop 0
	v_addc_co_u32_e32 v23, vcc, 0, v9, vcc
	v_add_co_u32_e32 v26, vcc, s18, v8
	s_mov_b32 s18, 0xbc000
	s_nop 0
	v_addc_co_u32_e32 v27, vcc, 0, v9, vcc
	v_add_co_u32_e32 v36, vcc, s18, v8
	s_mov_b32 s18, 0xc0000
	s_nop 0
	v_addc_co_u32_e32 v37, vcc, 0, v9, vcc
	global_load_dword v24, v[10:11], off nt
	global_load_dword v25, v[12:13], off nt
	global_load_dword v20, v[14:15], off nt
	global_load_dword v21, v[16:17], off nt
	s_nop 0
	global_load_dword v14, v[18:19], off nt
	global_load_dword v15, v[22:23], off nt
	s_nop 0
	global_load_dword v26, v[26:27], off nt
	s_nop 0
	global_load_dword v27, v[36:37], off nt
	v_add_co_u32_e32 v10, vcc, s18, v8
	s_mov_b32 s18, 0xc4000
	s_nop 0
	v_addc_co_u32_e32 v11, vcc, 0, v9, vcc
	v_add_co_u32_e32 v12, vcc, s18, v8
	s_mov_b32 s18, 0xc8000
	s_nop 0
	v_addc_co_u32_e32 v13, vcc, 0, v9, vcc
	v_add_co_u32_e32 v16, vcc, s18, v8
	s_mov_b32 s18, 0xcc000
	s_nop 0
	v_addc_co_u32_e32 v17, vcc, 0, v9, vcc
	v_add_co_u32_e32 v22, vcc, s18, v8
	s_mov_b32 s18, 0xd0000
	s_nop 0
	v_addc_co_u32_e32 v23, vcc, 0, v9, vcc
	v_add_co_u32_e32 v36, vcc, s18, v8
	s_mov_b32 s18, 0xd4000
	s_nop 0
	v_addc_co_u32_e32 v37, vcc, 0, v9, vcc
	v_add_co_u32_e32 v38, vcc, s18, v8
	s_mov_b32 s18, 0xd8000
	s_nop 0
	v_addc_co_u32_e32 v39, vcc, 0, v9, vcc
	v_add_co_u32_e32 v40, vcc, s18, v8
	s_mov_b32 s18, 0xdc000
	s_nop 0
	v_addc_co_u32_e32 v41, vcc, 0, v9, vcc
	v_add_co_u32_e32 v42, vcc, s18, v8
	s_mov_b32 s18, 0xe0000
	s_nop 0
	v_addc_co_u32_e32 v43, vcc, 0, v9, vcc
	global_load_dword v18, v[10:11], off nt
	global_load_dword v19, v[12:13], off nt
	s_nop 0
	global_load_dword v12, v[16:17], off nt
	global_load_dword v13, v[22:23], off nt
	s_nop 0
	global_load_dword v36, v[36:37], off nt
	s_nop 0
	global_load_dword v37, v[38:39], off nt
	global_load_dword v22, v[40:41], off nt
	global_load_dword v23, v[42:43], off nt
	v_add_co_u32_e32 v10, vcc, s18, v8
	s_mov_b32 s18, 0xe4000
	s_nop 0
	v_addc_co_u32_e32 v11, vcc, 0, v9, vcc
	v_add_co_u32_e32 v16, vcc, s18, v8
	s_mov_b32 s18, 0xe8000
	s_nop 0
	v_addc_co_u32_e32 v17, vcc, 0, v9, vcc
	v_add_co_u32_e32 v38, vcc, s18, v8
	s_mov_b32 s18, 0xec000
	s_nop 0
	v_addc_co_u32_e32 v39, vcc, 0, v9, vcc
	v_add_co_u32_e32 v40, vcc, s18, v8
	s_mov_b32 s18, 0xf0000
	s_nop 0
	v_addc_co_u32_e32 v41, vcc, 0, v9, vcc
	v_add_co_u32_e32 v42, vcc, s18, v8
	s_nop 1
	v_addc_co_u32_e32 v43, vcc, 0, v9, vcc
	v_add_co_u32_e32 v44, vcc, 0xf4000, v8
	s_nop 1
	v_addc_co_u32_e32 v45, vcc, 0, v9, vcc
	v_add_co_u32_e32 v46, vcc, 0xf8000, v8
	s_nop 1
	v_addc_co_u32_e32 v47, vcc, 0, v9, vcc
	v_add_co_u32_e32 v48, vcc, 0xfc000, v8
	s_nop 1
	v_addc_co_u32_e32 v49, vcc, 0, v9, vcc
	global_load_dword v8, v[10:11], off nt
	global_load_dword v9, v[16:17], off nt
	s_nop 0
	global_load_dword v10, v[38:39], off nt
	global_load_dword v11, v[40:41], off nt
	global_load_dword v16, v[42:43], off nt
	global_load_dword v17, v[44:45], off nt
	s_nop 0
	global_load_dword v38, v[46:47], off nt
	global_load_dword v39, v[48:49], off nt
	v_mov_b32_e32 v41, 1.0
	s_and_b64 vcc, exec, s[0:1]
	v_mov_b32_e32 v40, 1.0
	s_cbranch_vccnz .LBB0_246
	global_load_dword v40, v[6:7], off offset:128 nt
; DI void p0_weight_tile(const float* W, bf16_t* Bt, int N, const float* g, bool permute, int t, int lane) {
;     ...
;         for (int k = 0; k < 32; ++k) v[k] = src[(size_t)(32 * hh + k) * N];
; #pragma unroll
;         for (int k = 0; k < 32; ++k) v[k] *= (g ? g[k0 + 32 * hh + k] : 1.0f);
.LBB0_246:
	s_and_b64 vcc, exec, s[0:1]
	s_cbranch_vccnz .LBB0_248
	global_load_dword v41, v[6:7], off offset:132 nt
.LBB0_248:
	v_mov_b32_e32 v43, 1.0
	s_and_b64 vcc, exec, s[0:1]
	v_mov_b32_e32 v42, 1.0
	s_cbranch_vccnz .LBB0_250
	global_load_dword v42, v[6:7], off offset:136 nt
.LBB0_250:
	s_and_b64 vcc, exec, s[0:1]
	s_cbranch_vccnz .LBB0_252
	global_load_dword v43, v[6:7], off offset:140 nt
.LBB0_252:
	v_mov_b32_e32 v45, 1.0
	s_and_b64 vcc, exec, s[0:1]
	v_mov_b32_e32 v44, 1.0
	s_cbranch_vccnz .LBB0_254
	global_load_dword v44, v[6:7], off offset:144 nt
.LBB0_254:
	s_and_b64 vcc, exec, s[0:1]
	s_cbranch_vccnz .LBB0_256
	global_load_dword v45, v[6:7], off offset:148 nt
.LBB0_256:
	v_mov_b32_e32 v47, 1.0
	s_and_b64 vcc, exec, s[0:1]
	v_mov_b32_e32 v46, 1.0
	s_cbranch_vccnz .LBB0_258
	global_load_dword v46, v[6:7], off offset:152 nt
.LBB0_258:
	s_and_b64 vcc, exec, s[0:1]
	s_cbranch_vccnz .LBB0_260
	global_load_dword v47, v[6:7], off offset:156 nt
.LBB0_260:
	v_mov_b32_e32 v49, 1.0
	s_and_b64 vcc, exec, s[0:1]
	v_mov_b32_e32 v48, 1.0
	s_cbranch_vccnz .LBB0_262
	global_load_dword v48, v[6:7], off offset:160 nt
.LBB0_262:
	s_and_b64 vcc, exec, s[0:1]
	s_cbranch_vccnz .LBB0_264
	global_load_dword v49, v[6:7], off offset:164 nt
.LBB0_264:
	v_mov_b32_e32 v51, 1.0
	s_and_b64 vcc, exec, s[0:1]
	v_mov_b32_e32 v50, 1.0
	s_cbranch_vccnz .LBB0_266
	global_load_dword v50, v[6:7], off offset:168 nt
.LBB0_266:
	s_and_b64 vcc, exec, s[0:1]
	s_cbranch_vccnz .LBB0_268
	global_load_dword v51, v[6:7], off offset:172 nt
.LBB0_268:
	v_mov_b32_e32 v53, 1.0
	s_and_b64 vcc, exec, s[0:1]
	v_mov_b32_e32 v52, 1.0
	s_cbranch_vccnz .LBB0_270
	global_load_dword v52, v[6:7], off offset:176 nt
.LBB0_270:
	s_and_b64 vcc, exec, s[0:1]
	s_cbranch_vccnz .LBB0_272
	global_load_dword v53, v[6:7], off offset:180 nt
.LBB0_272:
	v_mov_b32_e32 v55, 1.0
	s_and_b64 vcc, exec, s[0:1]
	v_mov_b32_e32 v54, 1.0
	s_cbranch_vccnz .LBB0_274
	global_load_dword v54, v[6:7], off offset:184 nt
.LBB0_274:
	s_and_b64 vcc, exec, s[0:1]
	s_cbranch_vccnz .LBB0_276
	global_load_dword v55, v[6:7], off offset:188 nt
.LBB0_276:
	v_mov_b32_e32 v57, 1.0
	s_and_b64 vcc, exec, s[0:1]
	v_mov_b32_e32 v56, 1.0
	s_cbranch_vccnz .LBB0_278
	global_load_dword v56, v[6:7], off offset:192 nt
.LBB0_278:
	s_and_b64 vcc, exec, s[0:1]
	s_cbranch_vccnz .LBB0_280
	global_load_dword v57, v[6:7], off offset:196 nt
.LBB0_280:
	v_mov_b32_e32 v59, 1.0
	s_and_b64 vcc, exec, s[0:1]
	v_mov_b32_e32 v58, 1.0
	s_cbranch_vccnz .LBB0_282
	global_load_dword v58, v[6:7], off offset:200 nt
.LBB0_282:
	s_and_b64 vcc, exec, s[0:1]
	s_cbranch_vccnz .LBB0_284
	global_load_dword v59, v[6:7], off offset:204 nt
.LBB0_284:
	v_mov_b32_e32 v61, 1.0
	s_and_b64 vcc, exec, s[0:1]
	v_mov_b32_e32 v60, 1.0
	s_cbranch_vccnz .LBB0_286
	global_load_dword v60, v[6:7], off offset:208 nt
.LBB0_286:
	s_and_b64 vcc, exec, s[0:1]
	s_cbranch_vccnz .LBB0_288
	global_load_dword v61, v[6:7], off offset:212 nt
.LBB0_288:
	v_mov_b32_e32 v63, 1.0
	s_and_b64 vcc, exec, s[0:1]
	v_mov_b32_e32 v62, 1.0
	s_cbranch_vccnz .LBB0_290
	global_load_dword v62, v[6:7], off offset:216 nt
.LBB0_290:
	s_and_b64 vcc, exec, s[0:1]
	s_cbranch_vccnz .LBB0_292
	global_load_dword v63, v[6:7], off offset:220 nt
.LBB0_292:
	v_mov_b32_e32 v67, 1.0
	s_and_b64 vcc, exec, s[0:1]
	v_mov_b32_e32 v66, 1.0
	s_cbranch_vccnz .LBB0_294
	global_load_dword v66, v[6:7], off offset:224 nt
.LBB0_294:
	s_and_b64 vcc, exec, s[0:1]
	s_cbranch_vccnz .LBB0_296
	global_load_dword v67, v[6:7], off offset:228 nt
.LBB0_296:
	v_mov_b32_e32 v69, 1.0
	s_and_b64 vcc, exec, s[0:1]
	v_mov_b32_e32 v68, 1.0
	s_cbranch_vccnz .LBB0_298
	global_load_dword v68, v[6:7], off offset:232 nt
.LBB0_298:
	s_and_b64 vcc, exec, s[0:1]
	s_cbranch_vccnz .LBB0_300
	global_load_dword v69, v[6:7], off offset:236 nt
.LBB0_300:
	v_mov_b32_e32 v71, 1.0
	s_and_b64 vcc, exec, s[0:1]
	v_mov_b32_e32 v70, 1.0
	s_cbranch_vccnz .LBB0_302
	global_load_dword v70, v[6:7], off offset:240 nt
.LBB0_302:
	s_and_b64 vcc, exec, s[0:1]
	s_cbranch_vccnz .LBB0_304
	global_load_dword v71, v[6:7], off offset:244 nt
.LBB0_304:
	v_mov_b32_e32 v65, 1.0
	s_and_b64 vcc, exec, s[0:1]
	v_mov_b32_e32 v64, 1.0
	s_cbranch_vccnz .LBB0_306
	global_load_dword v64, v[6:7], off offset:248 nt
.LBB0_306:
	s_and_b64 vcc, exec, s[0:1]
	s_cbranch_vccnz .LBB0_39
	global_load_dword v65, v[6:7], off offset:252 nt
	s_branch .LBB0_39
